# mix2 chunk loop: top-of-loop barrier [A] executed only before the first chunk (moved into the preheader)
# speedup vs baseline: 1.0087x; 1.0087x over previous
; #define LAS __attribute__((address_space(3)))
; __device__ void mix_sweep(const Params& P, LAS unsigned char* lds, int tok0, int pos0, int seqlen, int hd, int dir, bool state_only, bool final_pass,
;                           f32x4 (&Cacc)[9], float& m_state, float& aseg_sum, float lgam) {
;     ...
;     LAS float* vrow = (LAS float*)(lds + VEC0); LAS float* vcol = vrow + 128; LAS float* vwi = vrow + 256; LAS float* vkw = vrow + 384; LAS float* vemt = vrow + 512; LAS float* vsc = vrow + 640;
;     const int qcol = is_m ? 2048 + h * 128 : h * 128, kcol = is_m ? 2560 + h * 128 : 512 + h * 128, vcolg = is_m ? 3072 + h * 128 : 1024 + h * 128;
;     const int gcol = is_m ? 3584 + h * 128 : 1536 + h * 128, mcol = is_m ? 512 + h * 128 : h * 128;
;     const float* gnw = (is_m ? P.in[11] : P.in[10]) + h * 128;
;     const float LOG2E = 1.4426950408889634f;
;     FragB FB; fragb_init(FB, w, fr, fg);
;     unsigned ktb0, ktb1; { const unsigned q = fr >> 2, p = fr & 3, L = (q << 2) | ((fg & 1u) << 1) | (p >> 1); ktb0 = 256u * (8u * fg + q) + 8u * (p & 1u) + 16u * (L ^ (2u * w)); ktb1 = 256u * (8u * fg + q) + 8u * (p & 1u) + 16u * (L ^ (2u * w + 1u)); asm volatile("" : "+v"(ktb0)); asm volatile("" : "+v"(ktb1)); }
;     __syncthreads();
;     if (!state_only) {
; #pragma unroll
;         for (int nt = 0; nt < 8; ++nt) { u32x2 v; v.x = cvt_pk_bf16(Cacc[nt][0], Cacc[nt][1]); v.y = cvt_pk_bf16(Cacc[nt][2], Cacc[nt][3]);
;             { LAUNDER_X16 *(LAS u32x2*)(lds + IMG_C + CWA(nt)) = v; } }
;         { u32x2 v; v.x = cvt_pk_bf16(Cacc[8][0], Cacc[8][1]); v.y = cvt_pk_bf16(Cacc[8][2], Cacc[8][3]); *(LAS u32x2*)(lds + IMG_CX + 32 * (16 * w + fr) + 8 * fg) = v; }
;     }
;     if (tid < 128) { unsigned zz = 0u; asm volatile("" : "+v"(zz)); u32x4 v0 = (u32x4){is_m ? 0x3F80u : zz, zz, zz, zz}; u32x4 z = (u32x4){zz, zz, zz, zz}; *(LAS u32x4*)(lds + IMG_VX + 32 * tid) = v0; *(LAS u32x4*)(lds + IMG_VX + 32 * tid + 16) = z; }
;     LAS float* PV = (LAS float*)(lds + 141888); LAS float* PS = PV + 8 * 3 * 128;
;     if (is_m) { const int c = dir ? 7 - w : w; const int tokc = tok0 + c * 128;
;         const int u0 = 2 * lane, u1 = 2 * lane + 1; const int j0 = dir ? 127 - u0 : u0, j1 = dir ? 127 - u1 : u1;
;         const float x0 = gates[(size_t)(tokc + j0) * 16 + 8 + dir * 4 + h], x1 = gates[(size_t)(tokc + j1) * 16 + 8 + dir * 4 + h];
.LBB0_96:
	s_and_b64 s[14:15], s[8:9], exec
	v_and_b32_e32 v0, 0x78, v0
	s_cselect_b32 s14, 0, 0x380
	v_lshlrev_b32_e32 v0, 1, v0
	s_or_b32 s14, s14, s79
	s_waitcnt lgkmcnt(2)
	v_lshl_add_u64 v[2:3], s[22:23], 0, v[0:1]
	v_ashrrev_i32_e32 v0, 4, v161
	v_add_u32_e32 v40, s14, v0
	v_add_u32_e32 v0, 0x200, v161
	v_ashrrev_i32_e32 v0, 4, v0
	v_add_u32_e32 v42, s14, v0
	v_add_u32_e32 v0, 0x400, v161
	v_ashrrev_i32_e32 v0, 4, v0
	v_add_u32_e32 v50, s14, v0
	v_add_u32_e32 v0, 0x600, v161
	v_ashrrev_i32_e32 v0, 4, v0
	v_add_u32_e32 v52, s14, v0
	v_ashrrev_i32_e32 v41, 31, v40
	s_lshl_b32 s38, s80, 1
	v_ashrrev_i32_e32 v43, 31, v42
	v_ashrrev_i32_e32 v51, 31, v50
	v_ashrrev_i32_e32 v53, 31, v52
	s_lshl_b32 s14, s81, 1
	s_mov_b32 s15, s39
	v_lshlrev_b64 v[56:57], 13, v[40:41]
	v_lshl_add_u64 v[48:49], v[2:3], 0, s[38:39]
	v_lshlrev_b64 v[58:59], 13, v[42:43]
	v_lshlrev_b64 v[64:65], 13, v[50:51]
	v_lshlrev_b64 v[66:67], 13, v[52:53]
	v_lshl_add_u64 v[2:3], v[2:3], 0, s[14:15]
	v_lshl_add_u64 v[40:41], v[48:49], 0, v[56:57]
	v_lshl_add_u64 v[44:45], v[48:49], 0, v[58:59]
	v_lshl_add_u64 v[50:51], v[48:49], 0, v[64:65]
	v_lshl_add_u64 v[52:53], v[48:49], 0, v[66:67]
	v_lshl_add_u64 v[56:57], v[2:3], 0, v[56:57]
	v_lshl_add_u64 v[60:61], v[2:3], 0, v[58:59]
	v_lshl_add_u64 v[64:65], v[2:3], 0, v[64:65]
	global_load_dwordx4 v[40:43], v[40:41], off
	s_nop 0
	global_load_dwordx4 v[44:47], v[44:45], off
	s_nop 0
	global_load_dwordx4 v[48:51], v[50:51], off
	s_nop 0
	global_load_dwordx4 v[52:55], v[52:53], off
	s_nop 0
	global_load_dwordx4 v[56:59], v[56:57], off
	s_nop 0
	global_load_dwordx4 v[60:63], v[60:61], off
	v_lshl_add_u64 v[2:3], v[2:3], 0, v[66:67]
	global_load_dwordx4 v[64:67], v[64:65], off
	s_nop 0
	global_load_dwordx4 v[68:71], v[2:3], off
	v_lshlrev_b32_e32 v79, 2, v161
	s_add_i32 s15, 0, 0x22000
	v_add_u32_e32 v182, s15, v79
	s_add_i32 s15, 0, 0x22200
	v_lshlrev_b32_e32 v0, 4, v73
	v_add_u32_e32 v183, s15, v79
	v_add_u32_e32 v190, s15, v0
	v_readlane_b32 s15, v253, 49
	s_add_i32 s19, 0, 0x22400
	v_add_u32_e32 v184, s19, v79
	v_add_u32_e32 v194, s15, v75
	s_add_i32 s15, 0, 0x1a000
	v_add_u32_e32 v195, s15, v75
	v_readlane_b32 s15, v253, 50
	s_add_i32 s19, 0, 0x22600
	s_add_i32 s46, 0, 0x22800
	v_add_u32_e32 v196, s15, v75
	s_add_i32 s15, 0, 0x1c000
	v_add_u32_e32 v197, s15, v75
	v_readlane_b32 s15, v253, 51
	v_lshlrev_b32_e32 v189, 2, v73
	v_mov_b32_e32 v73, v1
	v_add_u32_e32 v198, s15, v75
	s_add_i32 s15, 0, 0x1e000
	v_add_u32_e32 v199, s15, v75
	v_readlane_b32 s15, v253, 52
	s_add_i32 s85, 0, 0x10000
	s_mov_b32 s7, 0
	v_add_u32_e32 v200, s15, v75
	v_readlane_b32 s15, v253, 53
	s_mov_b32 s83, 1
	v_add_u32_e32 v185, s19, v79
	v_add_u32_e32 v247, s15, v75
	s_add_i32 s15, 0, 0x12000
	v_add_u32_e32 v248, s15, v75
	v_readlane_b32 s15, v253, 54
	v_add_u32_e32 v187, s46, v79
	v_cmp_eq_u32_e64 s[46:47], 0, v161
	v_add_u32_e32 v249, s15, v75
	s_add_i32 s15, 0, 0x14000
	v_add_u32_e32 v250, s15, v75
	v_readlane_b32 s15, v253, 55
	v_lshl_or_b32 v219, s16, 4, v169
	s_add_i32 s84, s17, 0
	v_add_u32_e32 v251, s15, v75
	s_add_i32 s15, 0, 0x16000
	v_add_u32_e32 v252, s15, v75
	v_readlane_b32 s15, v253, 56
	v_add_u32_e32 v191, 0, v78
	v_lshl_add_u32 v192, v72, 2, s19
	v_lshl_add_u64 v[2:3], s[2:3], 0, v[72:73]
	v_lshl_add_u64 v[152:153], s[4:5], 0, v[72:73]
	v_lshl_add_u64 v[154:155], s[94:95], 0, v[0:1]
	v_add_u32_e32 v193, s18, v75
	v_or_b32_e32 v201, 2, v189
	v_or_b32_e32 v202, 3, v189
	v_or_b32_e32 v204, 16, v189
	v_or_b32_e32 v205, 17, v189
	v_or_b32_e32 v206, 18, v189
	v_or_b32_e32 v207, 19, v189
	v_or_b32_e32 v222, 32, v189
	v_or_b32_e32 v223, 33, v189
	v_or_b32_e32 v224, 34, v189
	v_or_b32_e32 v225, 35, v189
	v_or_b32_e32 v226, 48, v189
	v_or_b32_e32 v227, 49, v189
	v_or_b32_e32 v228, 50, v189
	v_or_b32_e32 v229, 51, v189
	v_or_b32_e32 v230, 64, v189
	v_or_b32_e32 v231, 0x41, v189
	v_or_b32_e32 v232, 0x42, v189
	v_or_b32_e32 v233, 0x43, v189
	v_or_b32_e32 v234, 0x50, v189
	v_or_b32_e32 v235, 0x51, v189
	v_or_b32_e32 v236, 0x52, v189
	v_or_b32_e32 v237, 0x53, v189
	v_or_b32_e32 v238, 0x60, v189
	v_or_b32_e32 v239, 0x61, v189
	v_or_b32_e32 v240, 0x62, v189
	v_or_b32_e32 v241, 0x63, v189
	v_or_b32_e32 v242, 0x70, v189
	v_or_b32_e32 v243, 0x71, v189
	v_or_b32_e32 v244, 0x72, v189
	v_or_b32_e32 v245, 0x73, v189
	v_add_u32_e32 v246, s85, v75
	v_add_u32_e32 v211, s15, v75
	v_add_u32_e32 v164, 0, v79
	s_mov_b32 s86, 6
	s_movk_i32 s87, 0xd000
	v_add_u32_e32 v165, 0, v76
	v_add_u32_e32 v166, 0, v77
	v_add_u32_e32 v167, 0, v74
	v_readlane_b32 s88, v253, 57
	v_lshrrev_b32_e32 v80, 6, v161
	v_lshlrev_b32_e32 v80, 6, v80
	v_mov_b32_e32 v81, 0
	v_lshl_add_u64 v[82:83], v[154:155], 0, v[80:81]
	global_load_dwordx4 v[84:87], v[82:83], off
	v_bfe_u32 v81, v161, 4, 2
	v_lshl_add_u32 v80, v81, 4, v80
	v_add_u32_e32 v80, 0x25a80, v80
	s_waitcnt vmcnt(0)
	ds_write_b128 v80, v[84:87]
	s_waitcnt lgkmcnt(0)
	s_barrier
	s_branch .LBB0_98

; #define LAS __attribute__((address_space(3)))
; __device__ void mix_sweep(const Params& P, LAS unsigned char* lds, int tok0, int pos0, int seqlen, int hd, int dir, bool state_only, bool final_pass,
;                           f32x4 (&Cacc)[9], float& m_state, float& aseg_sum, float lgam) {
;     ...
;         const int c = dir ? 7 - ci : ci; const int tok = tok0 + c * 128;
;         __syncthreads();
;         int tl = tid; asm volatile("" : "+v"(tl));
;         if (!state_only) {
; #pragma unroll
;             for (int it = 0; it < 4; ++it) { const int item = tl + 512 * it, r = item >> 4, ch = item & 15; t[0][it] = *(const u32x4*)(proj + (size_t)(tok + r) * NPROJ + qcol + 8 * ch); } }
; #pragma unroll
;     ...
; #pragma unroll
;             for (int it = 0; it < 4; ++it) { const int item = tl + 512 * it, r = item >> 4, ch = item & 15; *(LAS u32x4*)(img + offb(r, ch)) = t[which][it]; } }
;         if (ci < 7) { const int cn = dir ? 6 - ci : ci + 1; const int tokn = tok0 + cn * 128;
; #pragma unroll
;             for (int which = 1; which < 3; ++which) { const int cb = which == 1 ? kcol : vcolg;
; #pragma unroll
;                 for (int it = 0; it < 4; ++it) { const int item = tl + 512 * it, r = item >> 4, ch = item & 15; t[which][it] = *(const u32x4*)(proj + (size_t)(tokn + r) * NPROJ + cb + 8 * ch); } } }
.LBB0_98:
	s_xor_b32 s15, s7, 0x380
	s_and_b64 s[16:17], s[8:9], exec
	s_cselect_b32 s89, s7, s15
	v_mov_b32_e32 v92, v161
	s_add_i32 s89, s89, s79
	s_waitcnt lgkmcnt(0)
	s_cmpk_eq_i32 s87, 0xfa00
	v_lshlrev_b32_e32 v0, 3, v92
	v_ashrrev_i32_e32 v72, 4, v92
	v_and_b32_e32 v0, 0x78, v0
	v_add_u32_e32 v74, s89, v72
	v_lshlrev_b32_e32 v0, 1, v0
	v_ashrrev_i32_e32 v75, 31, v74
	v_lshl_add_u64 v[88:89], s[36:37], 0, v[0:1]
	v_lshlrev_b64 v[74:75], 13, v[74:75]
	v_add_u32_e32 v73, 0x200, v92
	v_lshl_add_u64 v[74:75], v[88:89], 0, v[74:75]
	v_ashrrev_i32_e32 v73, 4, v73
	global_load_dwordx4 v[76:79], v[74:75], off
	v_add_u32_e32 v74, s89, v73
	v_ashrrev_i32_e32 v75, 31, v74
	v_lshlrev_b64 v[74:75], 13, v[74:75]
	v_lshl_add_u64 v[74:75], v[88:89], 0, v[74:75]
	global_load_dwordx4 v[80:83], v[74:75], off
	v_add_u32_e32 v74, 0x400, v92
	v_ashrrev_i32_e32 v74, 4, v74
	v_add_u32_e32 v75, 0x600, v92
	v_add_u32_e32 v84, s89, v74
	v_ashrrev_i32_e32 v75, 4, v75
	v_ashrrev_i32_e32 v85, 31, v84
	v_add_u32_e32 v90, s89, v75
	v_lshlrev_b64 v[84:85], 13, v[84:85]
	v_ashrrev_i32_e32 v91, 31, v90
	v_lshl_add_u64 v[84:85], v[88:89], 0, v[84:85]
	v_lshlrev_b64 v[90:91], 13, v[90:91]
	global_load_dwordx4 v[84:87], v[84:85], off
	v_lshl_add_u64 v[88:89], v[88:89], 0, v[90:91]
	global_load_dwordx4 v[88:91], v[88:89], off
	v_lshlrev_b32_e32 v94, 2, v72
	v_and_b32_e32 v92, 15, v92
	v_and_b32_e32 v94, 12, v94
	v_bfe_u32 v95, v72, 2, 2
	v_bitop3_b32 v94, v94, v92, v95 bitop3:0x36
	v_lshlrev_b32_e32 v96, 2, v73
	v_lshlrev_b32_e32 v93, 8, v72
	v_lshlrev_b32_e32 v94, 4, v94
	v_and_b32_e32 v96, 12, v96
	v_bfe_u32 v97, v73, 2, 2
	v_add3_u32 v95, s85, v94, v93
	v_bitop3_b32 v96, v96, v92, v97 bitop3:0x36
	v_lshlrev_b32_e32 v98, 2, v74
	s_waitcnt vmcnt(7)
	ds_write_b128 v95, v[56:59]
	v_lshlrev_b32_e32 v95, 8, v73
	v_lshlrev_b32_e32 v96, 4, v96
	v_and_b32_e32 v98, 12, v98
	v_bfe_u32 v99, v74, 2, 2
	v_add3_u32 v97, s85, v96, v95
	v_bitop3_b32 v98, v98, v92, v99 bitop3:0x36
	v_lshlrev_b32_e32 v100, 2, v75
	s_waitcnt vmcnt(6)
	ds_write_b128 v97, v[60:63]
	v_lshlrev_b32_e32 v97, 8, v74
	v_lshlrev_b32_e32 v98, 4, v98
	v_and_b32_e32 v100, 12, v100
	v_bfe_u32 v101, v75, 2, 2
	v_add3_u32 v99, s85, v98, v97
	v_bitop3_b32 v92, v100, v92, v101 bitop3:0x36
	s_waitcnt vmcnt(5)
	ds_write_b128 v99, v[64:67]
	v_lshlrev_b32_e32 v99, 8, v75
	v_lshlrev_b32_e32 v92, 4, v92
	v_add3_u32 v100, s85, v92, v99
	v_add3_u32 v93, 0, v94, v93
	v_add3_u32 v94, 0, v96, v95
	v_add3_u32 v95, 0, v98, v97
	v_add3_u32 v92, 0, v92, v99
	s_waitcnt vmcnt(4)
	ds_write_b128 v100, v[68:71]
	ds_write_b128 v93, v[40:43] offset:32768
	ds_write_b128 v94, v[44:47] offset:32768
	ds_write_b128 v95, v[48:51] offset:32768
	ds_write_b128 v92, v[52:55] offset:32768
	s_waitcnt vmcnt(3)
	ds_write_b128 v93, v[76:79]
	s_waitcnt vmcnt(2)
	ds_write_b128 v94, v[80:83]
	s_waitcnt vmcnt(1)
	ds_write_b128 v95, v[84:87]
	s_waitcnt vmcnt(0)
	ds_write_b128 v92, v[88:91]
	s_cbranch_scc1 .LBB0_100
	s_and_b64 s[16:17], s[8:9], exec
	s_cselect_b32 s15, s83, s86
	s_lshl_b32 s15, s15, 7
	s_add_i32 s15, s15, s79
	v_add_u32_e32 v40, s15, v72
	v_add_u32_e32 v42, s15, v73
	v_add_u32_e32 v50, s15, v74
	v_add_u32_e32 v52, s15, v75
	v_lshl_add_u64 v[56:57], s[22:23], 0, v[0:1]
	v_ashrrev_i32_e32 v41, 31, v40
	v_ashrrev_i32_e32 v43, 31, v42
	v_ashrrev_i32_e32 v51, 31, v50
	v_ashrrev_i32_e32 v53, 31, v52
	s_mov_b32 s15, s39
	v_lshlrev_b64 v[58:59], 13, v[40:41]
	v_lshl_add_u64 v[48:49], v[56:57], 0, s[38:39]
	v_lshlrev_b64 v[60:61], 13, v[42:43]
	v_lshlrev_b64 v[64:65], 13, v[50:51]
	v_lshlrev_b64 v[66:67], 13, v[52:53]
	v_lshl_add_u64 v[68:69], v[56:57], 0, s[14:15]
	v_lshl_add_u64 v[40:41], v[48:49], 0, v[58:59]
	v_lshl_add_u64 v[44:45], v[48:49], 0, v[60:61]
	v_lshl_add_u64 v[50:51], v[48:49], 0, v[64:65]
	v_lshl_add_u64 v[52:53], v[48:49], 0, v[66:67]
	v_lshl_add_u64 v[56:57], v[68:69], 0, v[58:59]
	v_lshl_add_u64 v[60:61], v[68:69], 0, v[60:61]
	v_lshl_add_u64 v[64:65], v[68:69], 0, v[64:65]
	v_lshl_add_u64 v[68:69], v[68:69], 0, v[66:67]
	global_load_dwordx4 v[40:43], v[40:41], off
	s_nop 0
	global_load_dwordx4 v[44:47], v[44:45], off
	s_nop 0
	global_load_dwordx4 v[48:51], v[50:51], off
	s_nop 0
	global_load_dwordx4 v[52:55], v[52:53], off
	s_nop 0
	global_load_dwordx4 v[56:59], v[56:57], off
	s_nop 0
	global_load_dwordx4 v[60:63], v[60:61], off
	s_nop 0
	global_load_dwordx4 v[64:67], v[64:65], off
	s_nop 0
	global_load_dwordx4 v[68:71], v[68:69], off
